# grid barrier: every arriving workgroup issues the L2 write-back before signalling arrival (early write-back)
# baseline (speedup 1.0000x reference)
; __device__ __forceinline__ unsigned xb_ld(unsigned* p)              { return __hip_atomic_load(p, __ATOMIC_RELAXED, __HIP_MEMORY_SCOPE_AGENT); }
; __device__ __forceinline__ unsigned xb_add(unsigned* p, unsigned v) { return __hip_atomic_fetch_add(p, v, __ATOMIC_RELAXED, __HIP_MEMORY_SCOPE_AGENT); }
; #define XB_SPIN(cond, bar) do { unsigned _sp = 0; while (cond) { __builtin_amdgcn_s_sleep(1); \
;     if ((++_sp & 255u) == 0u) { if (xb_ld(&(bar)[XB_TMO])) break; if (_sp > XB_SPIN_CAP) { atomicAdd(&(bar)[XB_TMO], 1u); break; } } } } while (0)
; __device__ __forceinline__ void xcd_barrier(const XcdBarrier& b, int tid) {
;     ...
;         unsigned* bar = b.bar; unsigned bx = b.x;
;         asm volatile("" : "+s"(bar), "+s"(bx));
;         __builtin_amdgcn_s_waitcnt(0);
;         unsigned nloc = b.st[0], nx = b.st[1];
;         if (nloc == 0u) { xcd_barrier_complete(bar, bx, nloc, nx); b.st[0] = nloc; b.st[1] = nx; }
;     ...
;         __builtin_amdgcn_fence(__ATOMIC_RELEASE, "agent");
;         asm volatile("s_waitcnt vmcnt(0)" ::: "memory");
;     ...
;         const unsigned old = xb_add(&bar[XB_XSUB(bx)], 1u);
;         const unsigned gen = old / nloc;
;         if (old + 1u == (gen + 1u) * nloc) {
;             __builtin_amdgcn_fence(__ATOMIC_RELEASE, "agent");
;             asm volatile("s_waitcnt vmcnt(0)" ::: "memory");
;             const unsigned og = xb_add(&bar[XB_TOP], 1u);
;             const unsigned tg = og / nx;
;             if (og + 1u == (tg + 1u) * nx) xb_add(&bar[XB_TOPGEN], 1u);
;             else XB_SPIN(xb_ld(&bar[XB_TOPGEN]) == tg, bar);
;             __builtin_amdgcn_fence(__ATOMIC_ACQUIRE, "agent");
;             xb_add(&bar[XB_XGEN(bx)], 1u);
;             asm volatile("s_waitcnt vmcnt(0)" ::: "memory");
;         } else {
;             XB_SPIN(xb_ld(&bar[XB_XGEN(bx)]) == gen, bar);
.LBB0_35:
	s_lshl_b32 s22, s33, 6
	s_add_i32 s4, s22, 0x500
	s_mov_b32 s5, 0
	s_lshl_b64 s[2:3], s[4:5], 2
	s_add_u32 s2, s34, s2
	s_addc_u32 s3, s35, s3
	v_mov_b32_e32 v1, 1
	v_mov_b64_e32 v[4:5], s[2:3]
	buffer_wbl2 sc1
	s_waitcnt vmcnt(0)
	flat_atomic_add v1, v[4:5], v1 sc0
	v_cvt_f32_u32_e32 v3, v2
	v_sub_u32_e32 v4, 0, v2
	v_rcp_iflag_f32_e32 v3, v3
	s_nop 0
	v_mul_f32_e32 v3, 0x4f7ffffe, v3
	v_cvt_u32_f32_e32 v3, v3
	v_mul_lo_u32 v4, v4, v3
	v_mul_hi_u32 v4, v3, v4
	v_add_u32_e32 v3, v3, v4
	s_waitcnt vmcnt(0) lgkmcnt(0)
	v_mul_hi_u32 v3, v1, v3
	v_mul_lo_u32 v5, v3, v2
	v_add_u32_e32 v4, 1, v1
	v_sub_u32_e32 v1, v1, v5
	v_add_u32_e32 v6, 1, v3
	v_cmp_ge_u32_e32 vcc, v1, v2
	v_sub_u32_e32 v5, v1, v2
	s_nop 0
	v_cndmask_b32_e32 v3, v3, v6, vcc
	v_cndmask_b32_e32 v1, v1, v5, vcc
	v_add_u32_e32 v5, 1, v3
	v_cmp_ge_u32_e32 vcc, v1, v2
	s_nop 1
	v_cndmask_b32_e32 v1, v3, v5, vcc
	v_mad_u64_u32 v[2:3], s[2:3], v2, v1, v[2:3]
	v_cmp_ne_u32_e32 vcc, v4, v2
	s_and_saveexec_b64 s[2:3], vcc
	s_xor_b64 s[2:3], exec, s[2:3]
	s_cbranch_execz .LBB0_48
	s_add_i32 s4, s22, 0x900
	s_lshl_b64 s[4:5], s[4:5], 2
	s_add_u32 s6, s34, s4
	s_addc_u32 s7, s35, s5
	v_mov_b64_e32 v[2:3], s[6:7]
	flat_load_dword v0, v[2:3] sc1
	s_waitcnt vmcnt(0) lgkmcnt(0)
	v_cmp_eq_u32_e32 vcc, v0, v1
	s_and_saveexec_b64 s[4:5], vcc
	s_cbranch_execz .LBB0_47
	s_mov_b32 s23, 1
	s_mov_b64 s[8:9], 0
	s_branch .LBB0_39

; __device__ __forceinline__ unsigned xb_ld(unsigned* p)              { return __hip_atomic_load(p, __ATOMIC_RELAXED, __HIP_MEMORY_SCOPE_AGENT); }
; __device__ __forceinline__ unsigned xb_add(unsigned* p, unsigned v) { return __hip_atomic_fetch_add(p, v, __ATOMIC_RELAXED, __HIP_MEMORY_SCOPE_AGENT); }
; #define XB_SPIN(cond, bar) do { unsigned _sp = 0; while (cond) { __builtin_amdgcn_s_sleep(1); \
;     if ((++_sp & 255u) == 0u) { if (xb_ld(&(bar)[XB_TMO])) break; if (_sp > XB_SPIN_CAP) { atomicAdd(&(bar)[XB_TMO], 1u); break; } } } } while (0)
; __device__ __forceinline__ void xcd_barrier(const XcdBarrier& b, int tid) {
;     ...
;         unsigned* bar = b.bar; unsigned bx = b.x;
;         asm volatile("" : "+s"(bar), "+s"(bx));
;         __builtin_amdgcn_s_waitcnt(0);
;         unsigned nloc = b.st[0], nx = b.st[1];
;         if (nloc == 0u) { xcd_barrier_complete(bar, bx, nloc, nx); b.st[0] = nloc; b.st[1] = nx; }
;     ...
;         __builtin_amdgcn_fence(__ATOMIC_RELEASE, "agent");
;         asm volatile("s_waitcnt vmcnt(0)" ::: "memory");
;     ...
;         const unsigned old = xb_add(&bar[XB_XSUB(bx)], 1u);
;         const unsigned gen = old / nloc;
;         if (old + 1u == (gen + 1u) * nloc) {
;             __builtin_amdgcn_fence(__ATOMIC_RELEASE, "agent");
;             asm volatile("s_waitcnt vmcnt(0)" ::: "memory");
;             const unsigned og = xb_add(&bar[XB_TOP], 1u);
;             const unsigned tg = og / nx;
;             if (og + 1u == (tg + 1u) * nx) xb_add(&bar[XB_TOPGEN], 1u);
;             else XB_SPIN(xb_ld(&bar[XB_TOPGEN]) == tg, bar);
;             __builtin_amdgcn_fence(__ATOMIC_ACQUIRE, "agent");
;             xb_add(&bar[XB_XGEN(bx)], 1u);
;             asm volatile("s_waitcnt vmcnt(0)" ::: "memory");
;         } else {
;             XB_SPIN(xb_ld(&bar[XB_XGEN(bx)]) == gen, bar);
.LBB0_201:
	s_lshl_b32 s22, s33, 6
	s_add_i32 s66, s22, 0x500
	s_lshl_b64 s[2:3], s[66:67], 2
	s_add_u32 s2, s34, s2
	s_addc_u32 s3, s35, s3
	v_mov_b64_e32 v[6:7], s[2:3]
	buffer_wbl2 sc1
	s_waitcnt vmcnt(0)
	flat_atomic_add v1, v[6:7], v237 sc0
	v_cvt_f32_u32_e32 v3, v4
	v_sub_u32_e32 v5, 0, v4
	v_rcp_iflag_f32_e32 v3, v3
	s_nop 0
	v_mul_f32_e32 v3, 0x4f7ffffe, v3
	v_cvt_u32_f32_e32 v3, v3
	v_mul_lo_u32 v5, v5, v3
	v_mul_hi_u32 v5, v3, v5
	v_add_u32_e32 v3, v3, v5
	s_waitcnt vmcnt(0) lgkmcnt(0)
	v_mul_hi_u32 v3, v1, v3
	v_mul_lo_u32 v5, v3, v4
	v_add_u32_e32 v6, 1, v1
	v_sub_u32_e32 v1, v1, v5
	v_add_u32_e32 v7, 1, v3
	v_cmp_ge_u32_e32 vcc, v1, v4
	v_sub_u32_e32 v5, v1, v4
	s_nop 0
	v_cndmask_b32_e32 v3, v3, v7, vcc
	v_cndmask_b32_e32 v1, v1, v5, vcc
	v_add_u32_e32 v5, 1, v3
	v_cmp_ge_u32_e32 vcc, v1, v4
	s_nop 1
	v_cndmask_b32_e32 v1, v3, v5, vcc
	v_mad_u64_u32 v[4:5], s[2:3], v4, v1, v[4:5]
	v_cmp_ne_u32_e32 vcc, v6, v4
	s_and_saveexec_b64 s[2:3], vcc
	s_xor_b64 s[2:3], exec, s[2:3]
	s_cbranch_execz .LBB0_214
	s_add_i32 s66, s22, 0x900
	s_lshl_b64 s[4:5], s[66:67], 2
	s_add_u32 s6, s34, s4
	s_addc_u32 s7, s35, s5
	v_mov_b64_e32 v[4:5], s[6:7]
	flat_load_dword v0, v[4:5] sc1
	s_waitcnt vmcnt(0) lgkmcnt(0)
	v_cmp_eq_u32_e32 vcc, v0, v1
	s_and_saveexec_b64 s[4:5], vcc
	s_cbranch_execz .LBB0_213
	s_mov_b32 s23, 1
	s_mov_b64 s[8:9], 0
	s_branch .LBB0_205

; __device__ __forceinline__ unsigned xb_ld(unsigned* p)              { return __hip_atomic_load(p, __ATOMIC_RELAXED, __HIP_MEMORY_SCOPE_AGENT); }
; __device__ __forceinline__ unsigned xb_add(unsigned* p, unsigned v) { return __hip_atomic_fetch_add(p, v, __ATOMIC_RELAXED, __HIP_MEMORY_SCOPE_AGENT); }
; #define XB_SPIN(cond, bar) do { unsigned _sp = 0; while (cond) { __builtin_amdgcn_s_sleep(1); \
;     if ((++_sp & 255u) == 0u) { if (xb_ld(&(bar)[XB_TMO])) break; if (_sp > XB_SPIN_CAP) { atomicAdd(&(bar)[XB_TMO], 1u); break; } } } } while (0)
; __device__ __forceinline__ void xcd_barrier(const XcdBarrier& b, int tid) {
;     ...
;         unsigned* bar = b.bar; unsigned bx = b.x;
;         asm volatile("" : "+s"(bar), "+s"(bx));
;         __builtin_amdgcn_s_waitcnt(0);
;         unsigned nloc = b.st[0], nx = b.st[1];
;         if (nloc == 0u) { xcd_barrier_complete(bar, bx, nloc, nx); b.st[0] = nloc; b.st[1] = nx; }
;     ...
;         __builtin_amdgcn_fence(__ATOMIC_RELEASE, "agent");
;         asm volatile("s_waitcnt vmcnt(0)" ::: "memory");
;     ...
;         const unsigned old = xb_add(&bar[XB_XSUB(bx)], 1u);
;         const unsigned gen = old / nloc;
;         if (old + 1u == (gen + 1u) * nloc) {
;             __builtin_amdgcn_fence(__ATOMIC_RELEASE, "agent");
;             asm volatile("s_waitcnt vmcnt(0)" ::: "memory");
;             const unsigned og = xb_add(&bar[XB_TOP], 1u);
;             const unsigned tg = og / nx;
;             if (og + 1u == (tg + 1u) * nx) xb_add(&bar[XB_TOPGEN], 1u);
;             else XB_SPIN(xb_ld(&bar[XB_TOPGEN]) == tg, bar);
;             __builtin_amdgcn_fence(__ATOMIC_ACQUIRE, "agent");
;             xb_add(&bar[XB_XGEN(bx)], 1u);
;             asm volatile("s_waitcnt vmcnt(0)" ::: "memory");
;         } else {
;             XB_SPIN(xb_ld(&bar[XB_XGEN(bx)]) == gen, bar);
.LBB0_266:
	s_lshl_b32 s22, s33, 6
	s_add_i32 s66, s22, 0x500
	s_lshl_b64 s[2:3], s[66:67], 2
	s_add_u32 s2, s34, s2
	s_addc_u32 s3, s35, s3
	v_mov_b64_e32 v[6:7], s[2:3]
	buffer_wbl2 sc1
	s_waitcnt vmcnt(0)
	flat_atomic_add v3, v[6:7], v237 sc0
	v_cvt_f32_u32_e32 v1, v4
	v_sub_u32_e32 v5, 0, v4
	v_rcp_iflag_f32_e32 v1, v1
	s_nop 0
	v_mul_f32_e32 v1, 0x4f7ffffe, v1
	v_cvt_u32_f32_e32 v1, v1
	v_mul_lo_u32 v5, v5, v1
	v_mul_hi_u32 v5, v1, v5
	v_add_u32_e32 v1, v1, v5
	s_waitcnt vmcnt(0) lgkmcnt(0)
	v_mul_hi_u32 v1, v3, v1
	v_mul_lo_u32 v5, v1, v4
	v_sub_u32_e32 v5, v3, v5
	v_cmp_ge_u32_e32 vcc, v5, v4
	v_add_u32_e32 v6, 1, v1
	v_add_u32_e32 v3, 1, v3
	v_cndmask_b32_e32 v1, v1, v6, vcc
	v_sub_u32_e32 v6, v5, v4
	v_cndmask_b32_e32 v5, v5, v6, vcc
	v_cmp_ge_u32_e32 vcc, v5, v4
	v_add_u32_e32 v5, 1, v1
	s_nop 0
	v_cndmask_b32_e32 v1, v1, v5, vcc
	v_mad_u64_u32 v[4:5], s[2:3], v4, v1, v[4:5]
	v_cmp_ne_u32_e32 vcc, v3, v4
	s_and_saveexec_b64 s[2:3], vcc
	s_xor_b64 s[2:3], exec, s[2:3]
	s_cbranch_execz .LBB0_279
	s_add_i32 s66, s22, 0x900
	s_lshl_b64 s[4:5], s[66:67], 2
	s_add_u32 s6, s34, s4
	s_addc_u32 s7, s35, s5
	v_mov_b64_e32 v[4:5], s[6:7]
	flat_load_dword v0, v[4:5] sc1
	s_waitcnt vmcnt(0) lgkmcnt(0)
	v_cmp_eq_u32_e32 vcc, v0, v1
	s_and_saveexec_b64 s[4:5], vcc
	s_cbranch_execz .LBB0_278
	s_mov_b32 s23, 1
	s_mov_b64 s[8:9], 0
	s_branch .LBB0_270
